# MLA: V-tile prefetch issued at tile start into dedicated registers (was mid-tile), a full tile of latency cover before the tail wait
# speedup vs baseline: 1.0173x; 1.0037x over previous
.LBB0_1373:
	s_or_b64 exec, exec, s[0:1]
	s_add_i32 s27, s27, 1
	s_mulk_i32 s43, 0x2800
	v_add_u32_e32 v72, s43, v174
	s_cmp_lg_u32 s27, 35
	s_waitcnt vmcnt(0)
	ds_write_b128 v72, v[232:235] offset:26624
	s_waitcnt lgkmcnt(0)
	s_barrier
	s_cbranch_scc0 .LBB0_1380

.LBB0_1376:
	s_or_b64 exec, exec, s[0:1]
	v_lshl_add_u64 v[232:233], v[216:217], 0, s[100:101]
	global_load_dwordx4 v[232:235], v[232:233], off offset:128
	s_and_b32 s0, s27, 1
	s_mul_i32 s1, s0, 0x3400
	v_add_u32_e32 v124, s1, v175
	ds_read_b128 v[76:79], v124
	ds_read_b128 v[88:91], v124 offset:64
	s_waitcnt lgkmcnt(1)
	v_mfma_f32_16x16x32_bf16 v[92:95], v[76:79], v[20:23], v[218:221]
	ds_read_b128 v[96:99], v124 offset:3328
	ds_read_b128 v[100:103], v124 offset:128
	ds_read_b128 v[108:111], v124 offset:6656
	ds_read_b128 v[112:115], v124 offset:6720
	ds_read_b128 v[120:123], v124 offset:9984
	ds_read_b128 v[182:185], v124 offset:6784
	v_mfma_f32_16x16x32_bf16 v[76:79], v[76:79], v[24:27], v[222:225]
	s_mul_i32 s1, s0, 0x2800
	s_waitcnt lgkmcnt(5)
	v_mfma_f32_16x16x32_bf16 v[104:107], v[96:99], v[20:23], v[218:221]
	v_mfma_f32_16x16x32_bf16 v[96:99], v[96:99], v[24:27], v[222:225]
	s_waitcnt lgkmcnt(3)
	v_mfma_f32_16x16x32_bf16 v[116:119], v[108:111], v[20:23], v[218:221]
	v_mfma_f32_16x16x32_bf16 v[108:111], v[108:111], v[24:27], v[222:225]
	s_waitcnt lgkmcnt(1)
	v_mfma_f32_16x16x32_bf16 v[80:83], v[120:123], v[20:23], v[218:221]
	v_mfma_f32_16x16x32_bf16 v[84:87], v[120:123], v[24:27], v[222:225]
	v_mfma_f32_16x16x32_bf16 v[92:95], v[88:91], v[12:15], v[92:95]
	v_mfma_f32_16x16x32_bf16 v[76:79], v[88:91], v[16:19], v[76:79]
	ds_read_b128 v[88:91], v124 offset:3392
	ds_read_b128 v[120:123], v124 offset:3456
	s_waitcnt lgkmcnt(1)
	v_mfma_f32_16x16x32_bf16 v[104:107], v[88:91], v[12:15], v[104:107]
	v_mfma_f32_16x16x32_bf16 v[88:91], v[88:91], v[16:19], v[96:99]
	s_nop 2
	ds_read_b128 v[96:99], v124 offset:10048
	ds_read_b128 v[190:193], v124 offset:10112
	s_waitcnt lgkmcnt(1)
	v_mfma_f32_16x16x32_bf16 v[194:197], v[96:99], v[12:15], v[80:83]
	s_nop 2
	v_mfma_f32_16x16x32_bf16 v[128:131], v[100:103], v[4:7], v[76:79]
	v_add_u32_e32 v82, s1, v176
	s_nop 1
	v_mfma_f32_16x16x32_bf16 v[116:119], v[112:115], v[12:15], v[116:119]
	v_mfma_f32_16x16x32_bf16 v[186:189], v[112:115], v[16:19], v[108:111]
	v_mfma_f32_16x16x32_bf16 v[198:201], v[96:99], v[16:19], v[84:87]
	ds_read_b64_tr_b16 v[124:125], v82 offset:26624
	ds_read_b64_tr_b16 v[112:113], v82 offset:26656
	ds_read_b64_tr_b16 v[108:109], v82 offset:26688
	ds_read_b64_tr_b16 v[96:97], v82 offset:26720
	ds_read_b64_tr_b16 v[126:127], v82 offset:29184
	ds_read_b64_tr_b16 v[114:115], v82 offset:29216
	ds_read_b64_tr_b16 v[110:111], v82 offset:29248
	ds_read_b64_tr_b16 v[98:99], v82 offset:29280
	v_mfma_f32_16x16x32_bf16 v[136:139], v[100:103], v[8:11], v[92:95]
	v_mfma_f32_16x16x32_bf16 v[132:135], v[120:123], v[4:7], v[88:91]
	s_nop 1
	ds_read_b64_tr_b16 v[92:93], v82 offset:31744
	ds_read_b64_tr_b16 v[88:89], v82 offset:31776
	ds_read_b64_tr_b16 v[84:85], v82 offset:31808
	ds_read_b64_tr_b16 v[80:81], v82 offset:31840
	ds_read_b64_tr_b16 v[94:95], v82 offset:34304
	ds_read_b64_tr_b16 v[90:91], v82 offset:34336
	ds_read_b64_tr_b16 v[86:87], v82 offset:34368
	ds_read_b64_tr_b16 v[82:83], v82 offset:34400
	v_mfma_f32_16x16x32_bf16 v[140:143], v[120:123], v[8:11], v[104:107]
	v_mfma_f32_16x16x32_bf16 v[116:119], v[182:185], v[8:11], v[116:119]
	v_mfma_f32_16x16x32_bf16 v[100:103], v[182:185], v[4:7], v[186:189]
	s_waitcnt lgkmcnt(14)
	v_mfma_f32_16x16x32_bf16 v[120:123], v[190:193], v[8:11], v[194:197]
	v_mfma_f32_16x16x32_bf16 v[104:107], v[190:193], v[4:7], v[198:201]
	v_max3_f32 v181, v136, v137, v138
	v_max3_f32 v183, v128, v129, v130
	v_max3_f32 v184, v131, v132, v133
	v_max3_f32 v181, v181, v139, v140
	v_max3_f32 v183, v183, v134, v135
	v_max3_f32 v181, v181, v141, v142
	v_max3_f32 v182, v143, v116, v117
	v_max3_f32 v184, v184, v100, v101
	v_max3_f32 v182, v182, v118, v119
	v_max3_f32 v184, v184, v102, v103
	v_max3_f32 v181, v181, v120, v121
	v_max3_f32 v182, v182, v122, v123
	v_max3_f32 v183, v183, v104, v105
	v_max3_f32 v184, v184, v106, v107
	v_max_f32_e32 v181, v181, v182
	v_max_f32_e32 v183, v183, v184
	v_max_f32_e32 v184, v181, v183
	v_cmp_lt_f32_e32 vcc, s36, v184
	s_cbranch_vccz .LBB0_1378
	v_mov_b32_e32 v182, v181
	v_mov_b32_e32 v184, v183
	s_nop 1
	v_permlane16_swap_b32_e32 v181, v182
	v_permlane16_swap_b32_e32 v183, v184
	v_max_f32_e32 v181, v181, v182
	v_max_f32_e32 v183, v183, v184
	v_mov_b32_e32 v182, v181
	v_mov_b32_e32 v184, v183
	s_nop 1
	v_permlane32_swap_b32_e32 v181, v182
	v_permlane32_swap_b32_e32 v183, v184
	v_max_f32_e32 v182, v181, v182
	v_max_f32_e32 v181, v183, v184
	v_max_f32_e32 v182, v182, v182
	v_max_f32_e32 v183, 0, v182
	v_exp_f32_e64 v182, -v183
	v_max_f32_e32 v181, v181, v181
	v_sub_f32_e32 v136, v136, v183
	v_sub_f32_e32 v137, v137, v183
	v_pk_mul_f32 v[70:71], v[70:71], v[182:183] op_sel_hi:[1,0]
	v_pk_mul_f32 v[68:69], v[68:69], v[182:183] op_sel_hi:[1,0]
	v_pk_mul_f32 v[62:63], v[62:63], v[182:183] op_sel_hi:[1,0]
	v_pk_mul_f32 v[60:61], v[60:61], v[182:183] op_sel_hi:[1,0]
	v_pk_mul_f32 v[54:55], v[54:55], v[182:183] op_sel_hi:[1,0]
	v_pk_mul_f32 v[52:53], v[52:53], v[182:183] op_sel_hi:[1,0]
	v_pk_mul_f32 v[46:47], v[46:47], v[182:183] op_sel_hi:[1,0]
	v_pk_mul_f32 v[44:45], v[44:45], v[182:183] op_sel_hi:[1,0]
	v_pk_mul_f32 v[38:39], v[38:39], v[182:183] op_sel_hi:[1,0]
	v_pk_mul_f32 v[36:37], v[36:37], v[182:183] op_sel_hi:[1,0]
	v_max_f32_e32 v182, 0, v181
	v_exp_f32_e64 v184, -v182
	v_sub_f32_e32 v138, v138, v183
	v_sub_f32_e32 v139, v139, v183
	v_sub_f32_e32 v140, v140, v183
	v_sub_f32_e32 v141, v141, v183
	v_sub_f32_e32 v142, v142, v183
	v_sub_f32_e32 v143, v143, v183
	v_sub_f32_e32 v116, v116, v183
	v_sub_f32_e32 v117, v117, v183
	v_sub_f32_e32 v118, v118, v183
	v_sub_f32_e32 v119, v119, v183
	v_sub_f32_e32 v120, v120, v183
	v_sub_f32_e32 v121, v121, v183
	v_sub_f32_e32 v122, v122, v183
	v_sub_f32_e32 v123, v123, v183
	v_pk_add_f32 v[158:159], v[158:159], v[182:183]
	v_xor_b32_e32 v218, 0x80000000, v159
	v_xor_b32_e32 v222, 0x80000000, v158
	v_mov_b32_e32 v219, v218
	v_mov_b32_e32 v220, v218
	v_mov_b32_e32 v221, v218
	v_mov_b32_e32 v223, v222
	v_mov_b32_e32 v224, v222
	v_mov_b32_e32 v225, v222
	v_sub_f32_e32 v128, v128, v182
	v_sub_f32_e32 v129, v129, v182
	v_sub_f32_e32 v130, v130, v182
	v_sub_f32_e32 v131, v131, v182
	v_sub_f32_e32 v132, v132, v182
	v_sub_f32_e32 v133, v133, v182
	v_sub_f32_e32 v134, v134, v182
	v_sub_f32_e32 v135, v135, v182
	v_sub_f32_e32 v100, v100, v182
	v_sub_f32_e32 v101, v101, v182
	v_sub_f32_e32 v102, v102, v182
	v_sub_f32_e32 v103, v103, v182
	v_sub_f32_e32 v104, v104, v182
	v_sub_f32_e32 v105, v105, v182
	v_sub_f32_e32 v106, v106, v182
	v_sub_f32_e32 v107, v107, v182
	v_pk_mul_f32 v[66:67], v[66:67], v[184:185] op_sel_hi:[1,0]
	v_pk_mul_f32 v[64:65], v[64:65], v[184:185] op_sel_hi:[1,0]
	v_pk_mul_f32 v[58:59], v[58:59], v[184:185] op_sel_hi:[1,0]
	v_pk_mul_f32 v[56:57], v[56:57], v[184:185] op_sel_hi:[1,0]
	v_pk_mul_f32 v[50:51], v[50:51], v[184:185] op_sel_hi:[1,0]
	v_pk_mul_f32 v[48:49], v[48:49], v[184:185] op_sel_hi:[1,0]
	v_pk_mul_f32 v[42:43], v[42:43], v[184:185] op_sel_hi:[1,0]
	v_pk_mul_f32 v[40:41], v[40:41], v[184:185] op_sel_hi:[1,0]
	v_pk_mul_f32 v[34:35], v[34:35], v[184:185] op_sel_hi:[1,0]
	v_pk_mul_f32 v[32:33], v[32:33], v[184:185] op_sel_hi:[1,0]
